# C + all eight GEMM K-loop heads padded to byte phase 0 mod 64 (code placement)
# speedup vs baseline: 1.0097x; 1.0073x over previous
;     __device__ bool next(int i, Unit& u) const { if (i != 0) return false; return so.next(round, u); }
;     __device__ __forceinline__ bool next(int i, Unit& u) const { if (i > 0 || !on) return false; u.pm = pm; u.pn = 0; return true; }
; template <class Epi, class Sched, bool ALIGN_EPI = false, bool SP2 = false, bool MIDHOOK = false>
; __device__ __forceinline__ void gemm_phase(PG8_LAS unsigned char* lds, const Gemm g, const Sched& S, const Epi& E) {
;     ...
;         const bool has_next = S.next(ui + 1, nxt);
;         const char* nA = has_next ? (const char*)g.A + (size_t)nxt.pm * tstep : cA; const char* nB = has_next ? (const char*)g.Bt + (size_t)nxt.pn * tstep : cB;
;         for (int t = 0; t < nt; t += 2) {
;             if constexpr (MIDHOOK) { if (t == nt / 2) E.mid(acc, cur, wr, wc, fr, fq); }
;             const bool last = (t == nt - 2);
;             const char* a1 = cA + (size_t)(t + 1) * kstep;
;             const char* a2 = last ? nA : cA + (size_t)(t + 2) * kstep; const char* b2 = last ? nB : cB + (size_t)(t + 2) * kstep;
;             const char* a3 = a2 + kstep; const char* b3 = b2 + kstep;
;     ...
; #pragma unroll
;         for (int a = 0; a < 2; ++a)
; #pragma unroll
;             for (int b = 0; b < 2; ++b)
; #pragma unroll
;                 for (int m = 0; m < 4; ++m)
; #pragma unroll
;                     for (int n = 0; n < 2; ++n) acc[a][b][m][n] = (f32x4){0.f, 0.f, 0.f, 0.f};
;         cur = nxt; cA = nA; cB = nB; ++ui;
.LBB0_190:
	s_ashr_i32 s41, s40, 31
	s_lshl_b64 s[42:43], s[40:41], 19
	v_readlane_b32 s12, v243, 48
	v_readlane_b32 s13, v243, 49
	s_add_u32 s42, s12, s42
	s_addc_u32 s43, s13, s43
	s_and_b64 s[44:45], s[0:1], exec
	s_cselect_b32 s5, s43, s7
	s_cselect_b32 s41, s42, s6
	s_ashr_i32 s39, s38, 31
	s_lshl_b64 s[44:45], s[38:39], 19
	s_add_u32 s44, s24, s44
	s_addc_u32 s45, s25, s45
	s_and_b64 s[48:49], s[0:1], exec
	s_cselect_b32 s39, s45, s9
	s_cselect_b32 s62, s44, s8
	s_add_u32 s6, s6, 0x40080
	s_addc_u32 s7, s7, 0
	s_add_u32 s63, s8, 0x100
	v_mov_b32_e32 v0, 0
	s_addc_u32 s64, s9, 0
	s_mov_b32 s65, -2
	v_mov_b32_e32 v1, v0
	v_mov_b32_e32 v2, v0
	v_mov_b32_e32 v3, v0
	v_mov_b32_e32 v8, v0
	v_mov_b32_e32 v9, v0
	v_mov_b32_e32 v10, v0
	v_mov_b32_e32 v11, v0
	v_mov_b32_e32 v16, v0
	v_mov_b32_e32 v17, v0
	v_mov_b32_e32 v18, v0
	v_mov_b32_e32 v19, v0
	v_mov_b32_e32 v24, v0
	v_mov_b32_e32 v25, v0
	v_mov_b32_e32 v26, v0
	v_mov_b32_e32 v27, v0
	v_mov_b32_e32 v32, v0
	v_mov_b32_e32 v33, v0
	v_mov_b32_e32 v34, v0
	v_mov_b32_e32 v35, v0
	v_mov_b32_e32 v40, v0
	v_mov_b32_e32 v41, v0
	v_mov_b32_e32 v42, v0
	v_mov_b32_e32 v43, v0
	v_mov_b32_e32 v48, v0
	v_mov_b32_e32 v49, v0
	v_mov_b32_e32 v50, v0
	v_mov_b32_e32 v51, v0
	v_mov_b32_e32 v56, v0
	v_mov_b32_e32 v57, v0
	v_mov_b32_e32 v58, v0
	v_mov_b32_e32 v59, v0
	v_mov_b32_e32 v4, v0
	v_mov_b32_e32 v5, v0
	v_mov_b32_e32 v6, v0
	v_mov_b32_e32 v7, v0
	v_mov_b32_e32 v12, v0
	v_mov_b32_e32 v13, v0
	v_mov_b32_e32 v14, v0
	v_mov_b32_e32 v15, v0
	v_mov_b32_e32 v20, v0
	v_mov_b32_e32 v21, v0
	v_mov_b32_e32 v22, v0
	v_mov_b32_e32 v23, v0
	v_mov_b32_e32 v28, v0
	v_mov_b32_e32 v29, v0
	v_mov_b32_e32 v30, v0
	v_mov_b32_e32 v31, v0
	v_mov_b32_e32 v36, v0
	v_mov_b32_e32 v37, v0
	v_mov_b32_e32 v38, v0
	v_mov_b32_e32 v39, v0
	v_mov_b32_e32 v44, v0
	v_mov_b32_e32 v45, v0
	v_mov_b32_e32 v46, v0
	v_mov_b32_e32 v47, v0
	v_mov_b32_e32 v52, v0
	v_mov_b32_e32 v53, v0
	v_mov_b32_e32 v54, v0
	v_mov_b32_e32 v55, v0
	v_mov_b32_e32 v60, v0
	v_mov_b32_e32 v61, v0
	v_mov_b32_e32 v62, v0
	v_mov_b32_e32 v63, v0
	v_mov_b32_e32 v64, v0
	v_mov_b32_e32 v65, v0
	v_mov_b32_e32 v66, v0
	v_mov_b32_e32 v67, v0
	v_mov_b32_e32 v72, v0
	v_mov_b32_e32 v73, v0
	v_mov_b32_e32 v74, v0
	v_mov_b32_e32 v75, v0
	v_mov_b32_e32 v80, v0
	v_mov_b32_e32 v81, v0
	v_mov_b32_e32 v82, v0
	v_mov_b32_e32 v83, v0
	v_mov_b32_e32 v88, v0
	v_mov_b32_e32 v89, v0
	v_mov_b32_e32 v90, v0
	v_mov_b32_e32 v91, v0
	v_mov_b32_e32 v96, v0
	v_mov_b32_e32 v97, v0
	v_mov_b32_e32 v98, v0
	v_mov_b32_e32 v99, v0
	v_mov_b32_e32 v104, v0
	v_mov_b32_e32 v105, v0
	v_mov_b32_e32 v106, v0
	v_mov_b32_e32 v107, v0
	v_mov_b32_e32 v112, v0
	v_mov_b32_e32 v113, v0
	v_mov_b32_e32 v114, v0
	v_mov_b32_e32 v115, v0
	v_mov_b32_e32 v120, v0
	v_mov_b32_e32 v121, v0
	v_mov_b32_e32 v122, v0
	v_mov_b32_e32 v123, v0
	v_mov_b32_e32 v68, v0
	v_mov_b32_e32 v69, v0
	v_mov_b32_e32 v70, v0
	v_mov_b32_e32 v71, v0
	v_mov_b32_e32 v76, v0
	v_mov_b32_e32 v77, v0
	v_mov_b32_e32 v78, v0
	v_mov_b32_e32 v79, v0
	v_mov_b32_e32 v84, v0
	v_mov_b32_e32 v85, v0
	v_mov_b32_e32 v86, v0
	v_mov_b32_e32 v87, v0
	v_mov_b32_e32 v92, v0
	v_mov_b32_e32 v93, v0
	v_mov_b32_e32 v94, v0
	v_mov_b32_e32 v95, v0
	v_mov_b32_e32 v100, v0
	v_mov_b32_e32 v101, v0
	v_mov_b32_e32 v102, v0
	v_mov_b32_e32 v103, v0
	v_mov_b32_e32 v108, v0
	v_mov_b32_e32 v109, v0
	v_mov_b32_e32 v110, v0
	v_mov_b32_e32 v111, v0
	v_mov_b32_e32 v116, v0
	v_mov_b32_e32 v117, v0
	v_mov_b32_e32 v118, v0
	v_mov_b32_e32 v119, v0
	v_mov_b32_e32 v124, v0
	v_mov_b32_e32 v125, v0
	v_mov_b32_e32 v126, v0
	v_mov_b32_e32 v127, v0
	s_nop 0
	s_nop 0
	s_nop 0
	s_nop 0
	s_nop 0
	s_nop 0

; #define PG8_STAGE(bufoff, gbase, voff) do { _Pragma("unroll") for (int _i = 0; _i < 2; ++_i) \
;         __builtin_amdgcn_global_load_lds((const unsigned*)((const char*)(gbase) + (voff)[_i]), (PG8_LAS unsigned*)(lds + (bufoff) + ldsw + _i * 8192), 16, 0, 0); } while (0)
; #define PG8_WAIT_V(n) asm volatile("s_waitcnt vmcnt(" #n ")" ::: "memory")
; #define PG8_BAR __builtin_amdgcn_s_barrier()
; template <class Epi, class Sched, bool ALIGN_EPI = false, bool SP2 = false, bool MIDHOOK = false>
; __device__ __forceinline__ void gemm_phase(PG8_LAS unsigned char* lds, const Gemm g, const Sched& S, const Epi& E) {
;     ...
;     f32x4 acc[2][2][4][2];
; #pragma unroll
;     for (int a = 0; a < 2; ++a)
; #pragma unroll
;         for (int b = 0; b < 2; ++b)
; #pragma unroll
;             for (int m = 0; m < 4; ++m)
; #pragma unroll
;                 for (int n = 0; n < 2; ++n) acc[a][b][m][n] = (f32x4){0.f, 0.f, 0.f, 0.f};
;     bf16x8 At[4][2], B0[2][2], B1[2][2];
;     const char* cA = (const char*)g.A + (size_t)cur.pm * tstep; const char* cB = (const char*)g.Bt + (size_t)cur.pn * tstep;
;     S.a_ready(cur);
;     if constexpr (SP2) {
;         PG8_STAGE(PG8_SB(0, 0), cB, voffB); PG8_STAGE(PG8_SB(0, 1), cB + hstep, voffB); PG8_STAGE(PG8_SA(0, 0), cA, voffA); PG8_STAGE(PG8_SA(0, 1), cA + hstep, voffA);
;         if (wr == 1) PG8_BAR;
;         PG8_WAIT_V(2); PG8_BAR;
;         PG8_STAGE(PG8_SB(1, 0), cB + kstep, voffB); PG8_STAGE(PG8_SA(1, 0), cA + kstep, voffA); PG8_STAGE(PG8_SB(1, 1), cB + hstep + kstep, voffB);
;         PG8_WAIT_V(6); PG8_BAR;
;     } else {
;         PG8_STAGE(PG8_SB(0, 0), cB, voffB); PG8_STAGE(PG8_SA(0, 0), cA, voffA); PG8_STAGE(PG8_SB(0, 1), cB + hstep, voffB); PG8_STAGE(PG8_SA(0, 1), cA + hstep, voffA);
;         if (wr == 1) PG8_BAR;
;         PG8_WAIT_V(4); PG8_BAR;
;         PG8_STAGE(PG8_SB(1, 0), cB + kstep, voffB); PG8_STAGE(PG8_SA(1, 0), cA + kstep, voffA); PG8_STAGE(PG8_SB(1, 1), cB + hstep + kstep, voffB);
;         PG8_WAIT_V(6); PG8_BAR;
;     }
.LBB0_373:
	v_and_b32_e32 v15, 15, v76
	v_and_b32_e32 v12, 0xfffffc00, v12
	v_lshl_or_b32 v77, s8, 6, v15
	v_lshl_add_u32 v17, s8, 13, v12
	s_mov_b64 s[8:9], 0x80
	s_add_i32 m0, s1, 0x18000
	v_lshl_add_u64 v[6:7], v[6:7], 0, s[8:9]
	s_and_b32 s39, s84, 3
	s_waitcnt vmcnt(2)
	s_barrier
	global_load_lds_dwordx4 v[6:7], off
	v_lshl_add_u64 v[4:5], v[4:5], 0, s[8:9]
	s_add_i32 m0, s1, 0x1a000
	s_add_i32 s42, s1, 0x8000
	s_add_i32 s43, s1, 0xa000
	global_load_lds_dwordx4 v[4:5], off
	v_lshl_add_u64 v[2:3], v[2:3], 0, s[8:9]
	s_mov_b32 m0, s42
	s_add_u32 s34, s4, 0x40080
	global_load_lds_dwordx4 v[2:3], off
	v_lshl_add_u64 v[0:1], v[0:1], 0, s[8:9]
	s_mov_b32 m0, s43
	s_addc_u32 s35, s5, 0
	s_add_i32 s44, s1, 0x1c000
	global_load_lds_dwordx4 v[0:1], off
	v_lshl_add_u64 v[0:1], s[34:35], 0, v[68:69]
	s_mov_b32 m0, s44
	s_add_i32 s45, s1, 0x1e000
	global_load_lds_dwordx4 v[0:1], off
	v_lshl_add_u64 v[0:1], s[34:35], 0, v[64:65]
	s_mov_b32 m0, s45
	s_add_u32 s24, s24, s28
	global_load_lds_dwordx4 v[0:1], off
	v_lshlrev_b32_e32 v0, 14, v11
	v_and_b32_e32 v0, 0xffff8000, v0
	s_addc_u32 s25, s25, 0
	v_lshl_add_u32 v0, v13, 11, v0
	v_and_b32_e32 v1, 1, v11
	s_add_u32 s24, s82, s24
	v_lshl_or_b32 v0, v1, 6, v0
	s_addc_u32 s25, s83, s25
	v_lshl_add_u32 v0, v14, 1, v0
	v_mov_b32_e32 v1, v69
	v_lshl_add_u64 v[0:1], s[24:25], 0, v[0:1]
	s_mov_b64 s[34:35], 0x17040080
	v_lshl_add_u64 v[72:73], v[0:1], 0, s[34:35]
	v_lshlrev_b32_e32 v0, 14, v8
	v_and_b32_e32 v16, 48, v76
	v_and_b32_e32 v0, 0xffff8000, v0
	v_lshl_or_b32 v15, v15, 6, v16
	v_lshlrev_b32_e32 v16, 2, v76
	v_lshl_add_u32 v0, v9, 11, v0
	v_and_b32_e32 v1, 1, v8
	v_and_b32_e32 v16, 32, v16
	v_lshl_add_u32 v12, s39, 12, v12
	v_lshl_or_b32 v0, v1, 6, v0
	s_add_u32 s46, s82, s28
	v_bitop3_b32 v12, v15, v12, v16 bitop3:0xde
	s_waitcnt vmcnt(6)
	v_lshl_add_u32 v0, v10, 1, v0
	v_mov_b32_e32 v1, v69
	s_addc_u32 s47, s83, 0
	s_add_i32 s51, 0, 0x10000
	s_add_i32 s53, 0, 0x18000
	v_bitop3_b32 v17, v15, v17, v16 bitop3:0xde
	v_lshl_add_u64 v[0:1], s[24:25], 0, v[0:1]
	v_add_u32_e32 v78, s51, v12
	s_add_i32 s51, s51, s30
	v_add_u32_e32 v80, s53, v12
	s_add_i32 s53, s53, s30
	v_lshl_add_u64 v[74:75], v[0:1], 0, s[34:35]
	s_mov_b32 s48, -2
	s_mov_b64 s[28:29], 0
	v_add_u32_e32 v79, 0, v17
	s_add_i32 s49, s1, 0xc000
	s_add_i32 s50, s1, 0xe000
	s_add_i32 s52, s51, 0x2000
	s_add_i32 s54, s53, 0x2000
	v_mov_b32_e32 v0, v69
	v_mov_b32_e32 v1, v69
	v_mov_b32_e32 v2, v69
	v_mov_b32_e32 v3, v69
	v_mov_b32_e32 v4, v69
	v_mov_b32_e32 v5, v69
	v_mov_b32_e32 v6, v69
	v_mov_b32_e32 v7, v69
	v_mov_b32_e32 v8, v69
	v_mov_b32_e32 v9, v69
	v_mov_b32_e32 v10, v69
	v_mov_b32_e32 v11, v69
	v_mov_b32_e32 v12, v69
	v_mov_b32_e32 v13, v69
	v_mov_b32_e32 v14, v69
	v_mov_b32_e32 v15, v69
	v_mov_b32_e32 v16, v69
	v_mov_b32_e32 v17, v69
	v_mov_b32_e32 v18, v69
	v_mov_b32_e32 v19, v69
	v_mov_b32_e32 v20, v69
	v_mov_b32_e32 v21, v69
	v_mov_b32_e32 v22, v69
	v_mov_b32_e32 v23, v69
	v_mov_b32_e32 v24, v69
	v_mov_b32_e32 v25, v69
	v_mov_b32_e32 v26, v69
	v_mov_b32_e32 v27, v69
	v_mov_b32_e32 v28, v69
	v_mov_b32_e32 v29, v69
	v_mov_b32_e32 v30, v69
	v_mov_b32_e32 v31, v69
	v_mov_b32_e32 v32, v69
	v_mov_b32_e32 v33, v69
	v_mov_b32_e32 v34, v69
	v_mov_b32_e32 v35, v69
	v_mov_b32_e32 v36, v69
	v_mov_b32_e32 v37, v69
	v_mov_b32_e32 v38, v69
	v_mov_b32_e32 v39, v69
	v_mov_b32_e32 v40, v69
	v_mov_b32_e32 v41, v69
	v_mov_b32_e32 v42, v69
	v_mov_b32_e32 v43, v69
	v_mov_b32_e32 v44, v69
	v_mov_b32_e32 v45, v69
	v_mov_b32_e32 v46, v69
	v_mov_b32_e32 v47, v69
	v_mov_b32_e32 v48, v69
	v_mov_b32_e32 v49, v69
	v_mov_b32_e32 v50, v69
	v_mov_b32_e32 v51, v69
	v_mov_b32_e32 v52, v69
	v_mov_b32_e32 v53, v69
	v_mov_b32_e32 v54, v69
	v_mov_b32_e32 v55, v69
	v_mov_b32_e32 v56, v69
	v_mov_b32_e32 v57, v69
	v_mov_b32_e32 v58, v69
	v_mov_b32_e32 v59, v69
	v_mov_b32_e32 v60, v69
	v_mov_b32_e32 v61, v69
	v_mov_b32_e32 v62, v69
	v_mov_b32_e32 v63, v69
	s_barrier
	s_waitcnt vmcnt(0)
	s_nop 0
	s_nop 0
	s_nop 0
	s_nop 0
	s_nop 0
	s_nop 0
	s_nop 0
	s_nop 0
	s_nop 0
	s_nop 0

;     __device__ bool next(int i, Unit& u) const { if (i != 0) return false; return so.next(round, u); }
;     __device__ __forceinline__ bool next(int i, Unit& u) const { if (i > 0 || !on) return false; u.pm = pm; u.pn = 0; return true; }
; template <class Epi, class Sched, bool ALIGN_EPI = false, bool SP2 = false, bool MIDHOOK = false>
; __device__ __forceinline__ void gemm_phase(PG8_LAS unsigned char* lds, const Gemm g, const Sched& S, const Epi& E) {
;     ...
;         const bool has_next = S.next(ui + 1, nxt);
;         const char* nA = has_next ? (const char*)g.A + (size_t)nxt.pm * tstep : cA; const char* nB = has_next ? (const char*)g.Bt + (size_t)nxt.pn * tstep : cB;
;         for (int t = 0; t < nt; t += 2) {
;             if constexpr (MIDHOOK) { if (t == nt / 2) E.mid(acc, cur, wr, wc, fr, fq); }
;             const bool last = (t == nt - 2);
;             const char* a1 = cA + (size_t)(t + 1) * kstep;
;             const char* a2 = last ? nA : cA + (size_t)(t + 2) * kstep; const char* b2 = last ? nB : cB + (size_t)(t + 2) * kstep;
;             const char* a3 = a2 + kstep; const char* b3 = b2 + kstep;
;     ...
; #pragma unroll
;         for (int a = 0; a < 2; ++a)
; #pragma unroll
;             for (int b = 0; b < 2; ++b)
; #pragma unroll
;                 for (int m = 0; m < 4; ++m)
; #pragma unroll
;                     for (int n = 0; n < 2; ++n) acc[a][b][m][n] = (f32x4){0.f, 0.f, 0.f, 0.f};
;         cur = nxt; cA = nA; cB = nB; ++ui;
.LBB0_3840:
	s_ashr_i32 s19, s18, 31
	s_lshl_b64 s[20:21], s[18:19], 19
	s_add_u32 s20, s68, s20
	s_addc_u32 s21, s69, s21
	s_and_b64 s[22:23], s[0:1], exec
	s_cselect_b32 s19, s21, s25
	s_cselect_b32 s46, s20, s24
	s_ashr_i32 s17, s16, 31
	s_lshl_b64 s[22:23], s[16:17], 19
	v_readlane_b32 s30, v243, 24
	v_readlane_b32 s31, v243, 25
	s_add_u32 s22, s30, s22
	s_addc_u32 s23, s31, s23
	s_and_b64 s[30:31], s[0:1], exec
	v_mov_b32_e32 v2, v0
	v_mov_b32_e32 v3, v0
	s_cselect_b32 s17, s23, s29
	s_cselect_b32 s47, s22, s28
	s_add_u32 s48, s28, 0x100
	v_mov_b32_e32 v1, v0
	v_mov_b64_e32 v[6:7], v[2:3]
	v_mov_b64_e32 v[10:11], v[2:3]
	v_mov_b64_e32 v[22:23], v[2:3]
	v_mov_b64_e32 v[26:27], v[2:3]
	v_mov_b64_e32 v[38:39], v[2:3]
	v_mov_b64_e32 v[42:43], v[2:3]
	v_mov_b64_e32 v[54:55], v[2:3]
	v_mov_b64_e32 v[58:59], v[2:3]
	v_mov_b64_e32 v[14:15], v[2:3]
	v_mov_b64_e32 v[18:19], v[2:3]
	v_mov_b64_e32 v[30:31], v[2:3]
	v_mov_b64_e32 v[34:35], v[2:3]
	v_mov_b64_e32 v[46:47], v[2:3]
	v_mov_b64_e32 v[50:51], v[2:3]
	v_mov_b64_e32 v[62:63], v[2:3]
	v_mov_b64_e32 v[66:67], v[2:3]
	v_mov_b64_e32 v[70:71], v[2:3]
	v_mov_b64_e32 v[74:75], v[2:3]
	v_mov_b64_e32 v[86:87], v[2:3]
	v_mov_b64_e32 v[90:91], v[2:3]
	v_mov_b64_e32 v[102:103], v[2:3]
	v_mov_b64_e32 v[106:107], v[2:3]
	v_mov_b64_e32 v[118:119], v[2:3]
	v_mov_b64_e32 v[122:123], v[2:3]
	v_mov_b64_e32 v[78:79], v[2:3]
	v_mov_b64_e32 v[82:83], v[2:3]
	v_mov_b64_e32 v[94:95], v[2:3]
	v_mov_b64_e32 v[98:99], v[2:3]
	v_mov_b64_e32 v[110:111], v[2:3]
	v_mov_b64_e32 v[114:115], v[2:3]
	v_mov_b64_e32 v[126:127], v[2:3]
	v_mov_b64_e32 v[130:131], v[2:3]
	v_lshl_add_u32 v204, s26, 8, v223
	v_lshl_add_u32 v206, s27, 8, v225
	v_lshl_add_u64 v[208:209], s[24:25], 0, v[196:197]
	v_lshl_add_u64 v[210:211], s[24:25], 0, v[198:199]
	s_addc_u32 s49, s29, 0
	s_mov_b32 s50, -2
	s_mov_b64 s[26:27], 0
	v_mov_b64_e32 v[4:5], v[0:1]
	v_mov_b64_e32 v[8:9], v[0:1]
	v_mov_b64_e32 v[20:21], v[0:1]
	v_mov_b64_e32 v[24:25], v[0:1]
	v_mov_b64_e32 v[36:37], v[0:1]
	v_mov_b64_e32 v[40:41], v[0:1]
	v_mov_b64_e32 v[52:53], v[0:1]
	v_mov_b64_e32 v[56:57], v[0:1]
	v_mov_b64_e32 v[12:13], v[0:1]
	v_mov_b64_e32 v[16:17], v[0:1]
	v_mov_b64_e32 v[28:29], v[0:1]
	v_mov_b64_e32 v[32:33], v[0:1]
	v_mov_b64_e32 v[44:45], v[0:1]
	v_mov_b64_e32 v[48:49], v[0:1]
	v_mov_b64_e32 v[60:61], v[0:1]
	v_mov_b64_e32 v[64:65], v[0:1]
	v_mov_b64_e32 v[68:69], v[0:1]
	v_mov_b64_e32 v[72:73], v[0:1]
	v_mov_b64_e32 v[84:85], v[0:1]
	v_mov_b64_e32 v[88:89], v[0:1]
	v_mov_b64_e32 v[100:101], v[0:1]
	v_mov_b64_e32 v[104:105], v[0:1]
	v_mov_b64_e32 v[116:117], v[0:1]
	v_mov_b64_e32 v[120:121], v[0:1]
	v_mov_b64_e32 v[76:77], v[0:1]
	v_mov_b64_e32 v[80:81], v[0:1]
	v_mov_b64_e32 v[92:93], v[0:1]
	v_mov_b64_e32 v[96:97], v[0:1]
	v_mov_b64_e32 v[108:109], v[0:1]
	v_mov_b64_e32 v[112:113], v[0:1]
	v_mov_b64_e32 v[124:125], v[0:1]
	v_mov_b64_e32 v[128:129], v[0:1]
	s_branch .LBB0_3842
	s_nop 0
	s_nop 0
	s_nop 0
	s_nop 0
	s_nop 0
	s_nop 0

; #define PG8_STAGE(bufoff, gbase, voff) do { _Pragma("unroll") for (int _i = 0; _i < 2; ++_i) \
;         __builtin_amdgcn_global_load_lds((const unsigned*)((const char*)(gbase) + (voff)[_i]), (PG8_LAS unsigned*)(lds + (bufoff) + ldsw + _i * 8192), 16, 0, 0); } while (0)
; #define PG8_WAIT_V(n) asm volatile("s_waitcnt vmcnt(" #n ")" ::: "memory")
; #define PG8_BAR __builtin_amdgcn_s_barrier()
; template <class Epi, class Sched, bool ALIGN_EPI = false, bool SP2 = false, bool MIDHOOK = false>
; __device__ __forceinline__ void gemm_phase(PG8_LAS unsigned char* lds, const Gemm g, const Sched& S, const Epi& E) {
;     ...
;     f32x4 acc[2][2][4][2];
; #pragma unroll
;     for (int a = 0; a < 2; ++a)
; #pragma unroll
;         for (int b = 0; b < 2; ++b)
; #pragma unroll
;             for (int m = 0; m < 4; ++m)
; #pragma unroll
;                 for (int n = 0; n < 2; ++n) acc[a][b][m][n] = (f32x4){0.f, 0.f, 0.f, 0.f};
;     bf16x8 At[4][2], B0[2][2], B1[2][2];
;     const char* cA = (const char*)g.A + (size_t)cur.pm * tstep; const char* cB = (const char*)g.Bt + (size_t)cur.pn * tstep;
;     S.a_ready(cur);
;     if constexpr (SP2) {
;         PG8_STAGE(PG8_SB(0, 0), cB, voffB); PG8_STAGE(PG8_SB(0, 1), cB + hstep, voffB); PG8_STAGE(PG8_SA(0, 0), cA, voffA); PG8_STAGE(PG8_SA(0, 1), cA + hstep, voffA);
;         if (wr == 1) PG8_BAR;
;         PG8_WAIT_V(2); PG8_BAR;
;         PG8_STAGE(PG8_SB(1, 0), cB + kstep, voffB); PG8_STAGE(PG8_SA(1, 0), cA + kstep, voffA); PG8_STAGE(PG8_SB(1, 1), cB + hstep + kstep, voffB);
;         PG8_WAIT_V(6); PG8_BAR;
;     } else {
;         PG8_STAGE(PG8_SB(0, 0), cB, voffB); PG8_STAGE(PG8_SA(0, 0), cA, voffA); PG8_STAGE(PG8_SB(0, 1), cB + hstep, voffB); PG8_STAGE(PG8_SA(0, 1), cA + hstep, voffA);
;         if (wr == 1) PG8_BAR;
;         PG8_WAIT_V(4); PG8_BAR;
;         PG8_STAGE(PG8_SB(1, 0), cB + kstep, voffB); PG8_STAGE(PG8_SA(1, 0), cA + kstep, voffA); PG8_STAGE(PG8_SB(1, 1), cB + hstep + kstep, voffB);
;         PG8_WAIT_V(6); PG8_BAR;
;     }
.LBB0_3911:
	s_mov_b64 s[12:13], 0x80
	s_add_i32 m0, s26, 0x18000
	v_lshl_add_u64 v[6:7], v[6:7], 0, s[12:13]
	s_and_b32 s11, s84, 3
	s_waitcnt vmcnt(2)
	s_barrier
	global_load_lds_dwordx4 v[6:7], off
	v_lshl_add_u64 v[4:5], v[4:5], 0, s[12:13]
	s_add_i32 m0, s26, 0x1a000
	s_add_i32 s31, s26, 0x8000
	s_add_i32 s33, s26, 0xa000
	global_load_lds_dwordx4 v[4:5], off
	v_lshl_add_u64 v[2:3], v[2:3], 0, s[12:13]
	s_mov_b32 m0, s31
	s_add_u32 s36, s6, 0x40080
	global_load_lds_dwordx4 v[2:3], off
	v_lshl_add_u64 v[0:1], v[0:1], 0, s[12:13]
	s_mov_b32 m0, s33
	s_addc_u32 s37, s7, 0
	global_load_lds_dwordx4 v[0:1], off
	s_add_i32 m0, s26, 0x1c000
	v_lshl_add_u64 v[0:1], s[36:37], 0, v[130:131]
	global_load_lds_dwordx4 v[0:1], off
	v_lshl_add_u64 v[0:1], s[36:37], 0, v[134:135]
	s_add_i32 m0, s26, 0x1e000
	s_add_u32 s22, s80, s22
	global_load_lds_dwordx4 v[0:1], off
	v_lshlrev_b32_e32 v0, 14, v8
	v_and_b32_e32 v0, 0xffff8000, v0
	v_lshl_add_u32 v0, v9, 11, v0
	v_and_b32_e32 v1, 1, v8
	v_lshl_or_b32 v0, v1, 6, v0
	v_lshl_add_u32 v0, v10, 1, v0
	v_mov_b32_e32 v1, v131
	s_addc_u32 s23, s81, s23
	s_mov_b64 s[34:35], 0x40080
	v_lshl_add_u64 v[0:1], s[22:23], 0, v[0:1]
	v_lshl_add_u64 v[136:137], v[0:1], 0, s[34:35]
	v_lshlrev_b32_e32 v0, 14, v11
	v_and_b32_e32 v0, 0xffff8000, v0
	v_lshl_add_u32 v0, v12, 11, v0
	v_and_b32_e32 v1, 1, v11
	v_lshl_or_b32 v0, v1, 6, v0
	v_and_b32_e32 v15, 15, v140
	v_and_b32_e32 v16, 48, v140
	v_lshl_add_u32 v0, v13, 1, v0
	v_mov_b32_e32 v1, v131
	s_add_u32 s16, s82, s16
	v_lshl_or_b32 v146, s30, 6, v15
	v_and_b32_e32 v14, 0xfffffc00, v14
	v_lshl_or_b32 v15, v15, 6, v16
	v_lshlrev_b32_e32 v16, 2, v140
	v_lshl_add_u64 v[0:1], s[22:23], 0, v[0:1]
	s_addc_u32 s17, s83, s17
	v_lshl_add_u32 v17, s30, 13, v14
	v_and_b32_e32 v16, 32, v16
	v_lshl_add_u32 v14, s11, 12, v14
	v_lshl_add_u64 v[138:139], v[0:1], 0, s[34:35]
	s_add_u32 s34, s16, 0xe00100
	v_bitop3_b32 v14, v15, v14, v16 bitop3:0xde
	s_waitcnt vmcnt(6)
	s_addc_u32 s35, s17, 0
	s_add_i32 s39, 0, 0x10000
	s_add_i32 s41, 0, 0x14000
	s_add_i32 s43, 0, 0x18000
	s_add_i32 s45, 0, 0x1c000
	v_bitop3_b32 v17, v15, v17, v16 bitop3:0xde
	v_add_u32_e32 v141, s39, v14
	v_add_u32_e32 v142, s41, v14
	s_add_i32 s39, s39, s24
	s_add_i32 s41, s41, s24
	v_add_u32_e32 v144, s43, v14
	v_add_u32_e32 v145, s45, v14
	s_add_i32 s43, s43, s24
	s_add_i32 s45, s45, s24
	s_mov_b32 s36, -2
	s_mov_b64 s[16:17], 0
	v_add_u32_e32 v143, 0, v17
	s_add_i32 s37, s26, 0xc000
	s_add_i32 s38, s26, 0xe000
	s_add_i32 s40, s39, 0x2000
	s_add_i32 s42, s41, 0x2000
	s_add_i32 s44, s43, 0x2000
	s_add_i32 s46, s45, 0x2000
	v_mov_b32_e32 v72, v131
	v_mov_b32_e32 v73, v131
	v_mov_b32_e32 v74, v131
	v_mov_b32_e32 v75, v131
	v_mov_b32_e32 v76, v131
	v_mov_b32_e32 v77, v131
	v_mov_b32_e32 v78, v131
	v_mov_b32_e32 v79, v131
	v_mov_b32_e32 v56, v131
	v_mov_b32_e32 v57, v131
	v_mov_b32_e32 v58, v131
	v_mov_b32_e32 v59, v131
	v_mov_b32_e32 v60, v131
	v_mov_b32_e32 v61, v131
	v_mov_b32_e32 v62, v131
	v_mov_b32_e32 v63, v131
	v_mov_b32_e32 v40, v131
	v_mov_b32_e32 v41, v131
	v_mov_b32_e32 v42, v131
	v_mov_b32_e32 v43, v131
	v_mov_b32_e32 v44, v131
	v_mov_b32_e32 v45, v131
	v_mov_b32_e32 v46, v131
	v_mov_b32_e32 v47, v131
	v_mov_b32_e32 v32, v131
	v_mov_b32_e32 v33, v131
	v_mov_b32_e32 v34, v131
	v_mov_b32_e32 v35, v131
	v_mov_b32_e32 v36, v131
	v_mov_b32_e32 v37, v131
	v_mov_b32_e32 v38, v131
	v_mov_b32_e32 v39, v131
	v_mov_b32_e32 v112, v131
	v_mov_b32_e32 v113, v131
	v_mov_b32_e32 v114, v131
	v_mov_b32_e32 v115, v131
	v_mov_b32_e32 v116, v131
	v_mov_b32_e32 v117, v131
	v_mov_b32_e32 v118, v131
	v_mov_b32_e32 v119, v131
	v_mov_b32_e32 v120, v131
	v_mov_b32_e32 v121, v131
	v_mov_b32_e32 v122, v131
	v_mov_b32_e32 v123, v131
	v_mov_b32_e32 v124, v131
	v_mov_b32_e32 v125, v131
	v_mov_b32_e32 v126, v131
	v_mov_b32_e32 v127, v131
	v_mov_b32_e32 v104, v131
	v_mov_b32_e32 v105, v131
	v_mov_b32_e32 v106, v131
	v_mov_b32_e32 v107, v131
	v_mov_b32_e32 v108, v131
	v_mov_b32_e32 v109, v131
	v_mov_b32_e32 v110, v131
	v_mov_b32_e32 v111, v131
	v_mov_b32_e32 v96, v131
	v_mov_b32_e32 v97, v131
	v_mov_b32_e32 v98, v131
	v_mov_b32_e32 v99, v131
	v_mov_b32_e32 v100, v131
	v_mov_b32_e32 v101, v131
	v_mov_b32_e32 v102, v131
	v_mov_b32_e32 v103, v131
	v_mov_b32_e32 v24, v131
	v_mov_b32_e32 v25, v131
	v_mov_b32_e32 v26, v131
	v_mov_b32_e32 v27, v131
	v_mov_b32_e32 v28, v131
	v_mov_b32_e32 v29, v131
	v_mov_b32_e32 v30, v131
	v_mov_b32_e32 v31, v131
	v_mov_b32_e32 v16, v131
	v_mov_b32_e32 v17, v131
	v_mov_b32_e32 v18, v131
	v_mov_b32_e32 v19, v131
	v_mov_b32_e32 v20, v131
	v_mov_b32_e32 v21, v131
	v_mov_b32_e32 v22, v131
	v_mov_b32_e32 v23, v131
	v_mov_b32_e32 v8, v131
	v_mov_b32_e32 v9, v131
	v_mov_b32_e32 v10, v131
	v_mov_b32_e32 v11, v131
	v_mov_b32_e32 v12, v131
	v_mov_b32_e32 v13, v131
	v_mov_b32_e32 v14, v131
	v_mov_b32_e32 v15, v131
	v_mov_b32_e32 v0, v131
	v_mov_b32_e32 v1, v131
	v_mov_b32_e32 v2, v131
	v_mov_b32_e32 v3, v131
	v_mov_b32_e32 v4, v131
	v_mov_b32_e32 v5, v131
	v_mov_b32_e32 v6, v131
	v_mov_b32_e32 v7, v131
	v_mov_b32_e32 v88, v131
	v_mov_b32_e32 v89, v131
	v_mov_b32_e32 v90, v131
	v_mov_b32_e32 v91, v131
	v_mov_b32_e32 v92, v131
	v_mov_b32_e32 v93, v131
	v_mov_b32_e32 v94, v131
	v_mov_b32_e32 v95, v131
	v_mov_b32_e32 v80, v131
	v_mov_b32_e32 v81, v131
	v_mov_b32_e32 v82, v131
	v_mov_b32_e32 v83, v131
	v_mov_b32_e32 v84, v131
	v_mov_b32_e32 v85, v131
	v_mov_b32_e32 v86, v131
	v_mov_b32_e32 v87, v131
	v_mov_b32_e32 v64, v131
	v_mov_b32_e32 v65, v131
	v_mov_b32_e32 v66, v131
	v_mov_b32_e32 v67, v131
	v_mov_b32_e32 v68, v131
	v_mov_b32_e32 v69, v131
	v_mov_b32_e32 v70, v131
	v_mov_b32_e32 v71, v131
	v_mov_b32_e32 v48, v131
	v_mov_b32_e32 v49, v131
	v_mov_b32_e32 v50, v131
	v_mov_b32_e32 v51, v131
	v_mov_b32_e32 v52, v131
	v_mov_b32_e32 v53, v131
	v_mov_b32_e32 v54, v131
	v_mov_b32_e32 v55, v131
	s_barrier
	s_nop 0
	s_nop 0
	s_nop 0
	s_nop 0
	s_nop 0
	s_nop 0

; #define PG8_STAGE(bufoff, gbase, voff) do { _Pragma("unroll") for (int _i = 0; _i < 2; ++_i) \
;         __builtin_amdgcn_global_load_lds((const unsigned*)((const char*)(gbase) + (voff)[_i]), (PG8_LAS unsigned*)(lds + (bufoff) + ldsw + _i * 8192), 16, 0, 0); } while (0)
; #define PG8_WAIT_V(n) asm volatile("s_waitcnt vmcnt(" #n ")" ::: "memory")
; #define PG8_BAR __builtin_amdgcn_s_barrier()
; template <class Epi, class Sched, bool ALIGN_EPI = false, bool SP2 = false, bool MIDHOOK = false>
; __device__ __forceinline__ void gemm_phase(PG8_LAS unsigned char* lds, const Gemm g, const Sched& S, const Epi& E) {
;     ...
;     f32x4 acc[2][2][4][2];
; #pragma unroll
;     for (int a = 0; a < 2; ++a)
; #pragma unroll
;         for (int b = 0; b < 2; ++b)
; #pragma unroll
;             for (int m = 0; m < 4; ++m)
; #pragma unroll
;                 for (int n = 0; n < 2; ++n) acc[a][b][m][n] = (f32x4){0.f, 0.f, 0.f, 0.f};
;     bf16x8 At[4][2], B0[2][2], B1[2][2];
;     const char* cA = (const char*)g.A + (size_t)cur.pm * tstep; const char* cB = (const char*)g.Bt + (size_t)cur.pn * tstep;
;     S.a_ready(cur);
;     if constexpr (SP2) {
;         PG8_STAGE(PG8_SB(0, 0), cB, voffB); PG8_STAGE(PG8_SB(0, 1), cB + hstep, voffB); PG8_STAGE(PG8_SA(0, 0), cA, voffA); PG8_STAGE(PG8_SA(0, 1), cA + hstep, voffA);
;         if (wr == 1) PG8_BAR;
;         PG8_WAIT_V(2); PG8_BAR;
;         PG8_STAGE(PG8_SB(1, 0), cB + kstep, voffB); PG8_STAGE(PG8_SA(1, 0), cA + kstep, voffA); PG8_STAGE(PG8_SB(1, 1), cB + hstep + kstep, voffB);
;         PG8_WAIT_V(6); PG8_BAR;
;     } else {
;         PG8_STAGE(PG8_SB(0, 0), cB, voffB); PG8_STAGE(PG8_SA(0, 0), cA, voffA); PG8_STAGE(PG8_SB(0, 1), cB + hstep, voffB); PG8_STAGE(PG8_SA(0, 1), cA + hstep, voffA);
;         if (wr == 1) PG8_BAR;
;         PG8_WAIT_V(4); PG8_BAR;
;         PG8_STAGE(PG8_SB(1, 0), cB + kstep, voffB); PG8_STAGE(PG8_SA(1, 0), cA + kstep, voffA); PG8_STAGE(PG8_SB(1, 1), cB + hstep + kstep, voffB);
;         PG8_WAIT_V(6); PG8_BAR;
;     }
.LBB0_3978:
	s_mov_b64 s[22:23], 0x80
	s_add_i32 m0, s30, 0x18000
	v_lshl_add_u64 v[6:7], v[6:7], 0, s[22:23]
	s_and_b32 s11, s84, 3
	s_waitcnt vmcnt(2)
	s_barrier
	global_load_lds_dwordx4 v[6:7], off
	v_lshl_add_u64 v[4:5], v[4:5], 0, s[22:23]
	s_add_i32 m0, s30, 0x1a000
	s_add_i32 s36, s30, 0x8000
	s_add_i32 s37, s30, 0xa000
	global_load_lds_dwordx4 v[4:5], off
	v_lshl_add_u64 v[2:3], v[2:3], 0, s[22:23]
	s_mov_b32 m0, s36
	s_add_u32 s40, s4, 0x40080
	global_load_lds_dwordx4 v[2:3], off
	v_lshl_add_u64 v[0:1], v[0:1], 0, s[22:23]
	s_mov_b32 m0, s37
	s_addc_u32 s41, s5, 0
	global_load_lds_dwordx4 v[0:1], off
	s_add_i32 m0, s30, 0x1c000
	v_lshl_add_u64 v[0:1], s[40:41], 0, v[130:131]
	global_load_lds_dwordx4 v[0:1], off
	v_lshl_add_u64 v[0:1], s[40:41], 0, v[134:135]
	s_add_i32 m0, s30, 0x1e000
	s_add_u32 s26, s80, s26
	global_load_lds_dwordx4 v[0:1], off
	v_lshlrev_b32_e32 v0, 14, v8
	v_and_b32_e32 v0, 0xffff8000, v0
	v_lshl_add_u32 v0, v9, 11, v0
	v_and_b32_e32 v1, 1, v8
	v_lshl_or_b32 v0, v1, 6, v0
	v_lshl_add_u32 v0, v10, 1, v0
	v_mov_b32_e32 v1, v131
	s_addc_u32 s27, s81, s27
	s_mov_b64 s[38:39], 0x40080
	v_lshl_add_u64 v[0:1], s[26:27], 0, v[0:1]
	v_lshl_add_u64 v[136:137], v[0:1], 0, s[38:39]
	v_lshlrev_b32_e32 v0, 14, v11
	v_and_b32_e32 v0, 0xffff8000, v0
	v_lshl_add_u32 v0, v12, 11, v0
	v_and_b32_e32 v1, 1, v11
	v_lshl_or_b32 v0, v1, 6, v0
	v_and_b32_e32 v15, 15, v140
	v_and_b32_e32 v16, 48, v140
	v_lshl_add_u32 v0, v13, 1, v0
	v_mov_b32_e32 v1, v131
	s_add_u32 s24, s82, s24
	v_lshl_or_b32 v146, s17, 6, v15
	v_and_b32_e32 v14, 0xfffffc00, v14
	v_lshl_or_b32 v15, v15, 6, v16
	v_lshlrev_b32_e32 v16, 2, v140
	v_lshl_add_u64 v[0:1], s[26:27], 0, v[0:1]
	s_addc_u32 s25, s83, s25
	v_lshl_add_u32 v17, s17, 13, v14
	v_and_b32_e32 v16, 32, v16
	v_lshl_add_u32 v14, s11, 12, v14
	v_lshl_add_u64 v[138:139], v[0:1], 0, s[38:39]
	s_add_u32 s38, s24, 0xe00100
	v_bitop3_b32 v14, v15, v14, v16 bitop3:0xde
	s_waitcnt vmcnt(6)
	s_addc_u32 s39, s25, 0
	s_add_i32 s43, 0, 0x10000
	s_add_i32 s45, 0, 0x14000
	s_add_i32 s47, 0, 0x18000
	s_add_i32 s49, 0, 0x1c000
	v_bitop3_b32 v17, v15, v17, v16 bitop3:0xde
	v_add_u32_e32 v141, s43, v14
	v_add_u32_e32 v142, s45, v14
	s_add_i32 s43, s43, s28
	s_add_i32 s45, s45, s28
	v_add_u32_e32 v144, s47, v14
	v_add_u32_e32 v145, s49, v14
	s_add_i32 s47, s47, s28
	s_add_i32 s49, s49, s28
	s_mov_b32 s40, -2
	s_mov_b64 s[24:25], 0
	v_add_u32_e32 v143, 0, v17
	s_add_i32 s41, s30, 0xc000
	s_add_i32 s42, s30, 0xe000
	s_add_i32 s44, s43, 0x2000
	s_add_i32 s46, s45, 0x2000
	s_add_i32 s48, s47, 0x2000
	s_add_i32 s50, s49, 0x2000
	v_mov_b32_e32 v72, v131
	v_mov_b32_e32 v73, v131
	v_mov_b32_e32 v74, v131
	v_mov_b32_e32 v75, v131
	v_mov_b32_e32 v76, v131
	v_mov_b32_e32 v77, v131
	v_mov_b32_e32 v78, v131
	v_mov_b32_e32 v79, v131
	v_mov_b32_e32 v56, v131
	v_mov_b32_e32 v57, v131
	v_mov_b32_e32 v58, v131
	v_mov_b32_e32 v59, v131
	v_mov_b32_e32 v60, v131
	v_mov_b32_e32 v61, v131
	v_mov_b32_e32 v62, v131
	v_mov_b32_e32 v63, v131
	v_mov_b32_e32 v40, v131
	v_mov_b32_e32 v41, v131
	v_mov_b32_e32 v42, v131
	v_mov_b32_e32 v43, v131
	v_mov_b32_e32 v44, v131
	v_mov_b32_e32 v45, v131
	v_mov_b32_e32 v46, v131
	v_mov_b32_e32 v47, v131
	v_mov_b32_e32 v32, v131
	v_mov_b32_e32 v33, v131
	v_mov_b32_e32 v34, v131
	v_mov_b32_e32 v35, v131
	v_mov_b32_e32 v36, v131
	v_mov_b32_e32 v37, v131
	v_mov_b32_e32 v38, v131
	v_mov_b32_e32 v39, v131
	v_mov_b32_e32 v112, v131
	v_mov_b32_e32 v113, v131
	v_mov_b32_e32 v114, v131
	v_mov_b32_e32 v115, v131
	v_mov_b32_e32 v116, v131
	v_mov_b32_e32 v117, v131
	v_mov_b32_e32 v118, v131
	v_mov_b32_e32 v119, v131
	v_mov_b32_e32 v120, v131
	v_mov_b32_e32 v121, v131
	v_mov_b32_e32 v122, v131
	v_mov_b32_e32 v123, v131
	v_mov_b32_e32 v124, v131
	v_mov_b32_e32 v125, v131
	v_mov_b32_e32 v126, v131
	v_mov_b32_e32 v127, v131
	v_mov_b32_e32 v104, v131
	v_mov_b32_e32 v105, v131
	v_mov_b32_e32 v106, v131
	v_mov_b32_e32 v107, v131
	v_mov_b32_e32 v108, v131
	v_mov_b32_e32 v109, v131
	v_mov_b32_e32 v110, v131
	v_mov_b32_e32 v111, v131
	v_mov_b32_e32 v96, v131
	v_mov_b32_e32 v97, v131
	v_mov_b32_e32 v98, v131
	v_mov_b32_e32 v99, v131
	v_mov_b32_e32 v100, v131
	v_mov_b32_e32 v101, v131
	v_mov_b32_e32 v102, v131
	v_mov_b32_e32 v103, v131
	v_mov_b32_e32 v24, v131
	v_mov_b32_e32 v25, v131
	v_mov_b32_e32 v26, v131
	v_mov_b32_e32 v27, v131
	v_mov_b32_e32 v28, v131
	v_mov_b32_e32 v29, v131
	v_mov_b32_e32 v30, v131
	v_mov_b32_e32 v31, v131
	v_mov_b32_e32 v16, v131
	v_mov_b32_e32 v17, v131
	v_mov_b32_e32 v18, v131
	v_mov_b32_e32 v19, v131
	v_mov_b32_e32 v20, v131
	v_mov_b32_e32 v21, v131
	v_mov_b32_e32 v22, v131
	v_mov_b32_e32 v23, v131
	v_mov_b32_e32 v8, v131
	v_mov_b32_e32 v9, v131
	v_mov_b32_e32 v10, v131
	v_mov_b32_e32 v11, v131
	v_mov_b32_e32 v12, v131
	v_mov_b32_e32 v13, v131
	v_mov_b32_e32 v14, v131
	v_mov_b32_e32 v15, v131
	v_mov_b32_e32 v0, v131
	v_mov_b32_e32 v1, v131
	v_mov_b32_e32 v2, v131
	v_mov_b32_e32 v3, v131
	v_mov_b32_e32 v4, v131
	v_mov_b32_e32 v5, v131
	v_mov_b32_e32 v6, v131
	v_mov_b32_e32 v7, v131
	v_mov_b32_e32 v88, v131
	v_mov_b32_e32 v89, v131
	v_mov_b32_e32 v90, v131
	v_mov_b32_e32 v91, v131
	v_mov_b32_e32 v92, v131
	v_mov_b32_e32 v93, v131
	v_mov_b32_e32 v94, v131
	v_mov_b32_e32 v95, v131
	v_mov_b32_e32 v80, v131
	v_mov_b32_e32 v81, v131
	v_mov_b32_e32 v82, v131
	v_mov_b32_e32 v83, v131
	v_mov_b32_e32 v84, v131
	v_mov_b32_e32 v85, v131
	v_mov_b32_e32 v86, v131
	v_mov_b32_e32 v87, v131
	v_mov_b32_e32 v64, v131
	v_mov_b32_e32 v65, v131
	v_mov_b32_e32 v66, v131
	v_mov_b32_e32 v67, v131
	v_mov_b32_e32 v68, v131
	v_mov_b32_e32 v69, v131
	v_mov_b32_e32 v70, v131
	v_mov_b32_e32 v71, v131
	v_mov_b32_e32 v48, v131
	v_mov_b32_e32 v49, v131
	v_mov_b32_e32 v50, v131
	v_mov_b32_e32 v51, v131
	v_mov_b32_e32 v52, v131
	v_mov_b32_e32 v53, v131
	v_mov_b32_e32 v54, v131
	v_mov_b32_e32 v55, v131
	s_barrier
	s_nop 0
	s_nop 0
	s_nop 0
	s_nop 0

;     __device__ bool next(int i, Unit& u) const { if (i != 0) return false; return so.next(round, u); }
;     __device__ __forceinline__ bool next(int i, Unit& u) const { if (i > 0 || !on) return false; u.pm = pm; u.pn = 0; return true; }
; template <class Epi, class Sched, bool ALIGN_EPI = false, bool SP2 = false, bool MIDHOOK = false>
; __device__ __forceinline__ void gemm_phase(PG8_LAS unsigned char* lds, const Gemm g, const Sched& S, const Epi& E) {
;     ...
;         const bool has_next = S.next(ui + 1, nxt);
;         const char* nA = has_next ? (const char*)g.A + (size_t)nxt.pm * tstep : cA; const char* nB = has_next ? (const char*)g.Bt + (size_t)nxt.pn * tstep : cB;
;     ...
; #pragma unroll
;         for (int a = 0; a < 2; ++a)
; #pragma unroll
;             for (int b = 0; b < 2; ++b)
; #pragma unroll
;                 for (int m = 0; m < 4; ++m)
; #pragma unroll
;                     for (int n = 0; n < 2; ++n) acc[a][b][m][n] = (f32x4){0.f, 0.f, 0.f, 0.f};
;         cur = nxt; cA = nA; cB = nB; ++ui;
.LBB0_4105:
	s_ashr_i32 s31, s30, 31
	s_lshl_b64 s[34:35], s[30:31], 19
	s_add_u32 s34, s14, s34
	s_addc_u32 s35, s15, s35
	s_and_b64 s[36:37], s[4:5], exec
	s_cselect_b32 s31, s35, s41
	s_cselect_b32 s60, s34, s40
	s_ashr_i32 s29, s28, 31
	s_lshl_b64 s[36:37], s[28:29], 19
	v_readlane_b32 s44, v243, 28
	v_readlane_b32 s45, v243, 29
	s_add_u32 s36, s44, s36
	s_addc_u32 s37, s45, s37
	s_and_b64 s[44:45], s[4:5], exec
	s_cselect_b32 s29, s37, s43
	s_cselect_b32 s61, s36, s42
	s_add_u32 s40, s40, 0x40080
	s_addc_u32 s41, s41, 0
	s_add_u32 s62, s42, 0x100
	v_mov_b32_e32 v0, 0
	s_addc_u32 s63, s43, 0
	s_mov_b32 s64, -2
	v_mov_b32_e32 v1, v0
	v_mov_b32_e32 v2, v0
	v_mov_b32_e32 v3, v0
	v_mov_b32_e32 v4, v0
	v_mov_b32_e32 v5, v0
	v_mov_b32_e32 v6, v0
	v_mov_b32_e32 v7, v0
	v_mov_b32_e32 v16, v0
	v_mov_b32_e32 v17, v0
	v_mov_b32_e32 v18, v0
	v_mov_b32_e32 v19, v0
	v_mov_b32_e32 v20, v0
	v_mov_b32_e32 v21, v0
	v_mov_b32_e32 v22, v0
	v_mov_b32_e32 v23, v0
	v_mov_b32_e32 v32, v0
	v_mov_b32_e32 v33, v0
	v_mov_b32_e32 v34, v0
	v_mov_b32_e32 v35, v0
	v_mov_b32_e32 v36, v0
	v_mov_b32_e32 v37, v0
	v_mov_b32_e32 v38, v0
	v_mov_b32_e32 v39, v0
	v_mov_b32_e32 v48, v0
	v_mov_b32_e32 v49, v0
	v_mov_b32_e32 v50, v0
	v_mov_b32_e32 v51, v0
	v_mov_b32_e32 v52, v0
	v_mov_b32_e32 v53, v0
	v_mov_b32_e32 v54, v0
	v_mov_b32_e32 v55, v0
	v_mov_b32_e32 v8, v0
	v_mov_b32_e32 v9, v0
	v_mov_b32_e32 v10, v0
	v_mov_b32_e32 v11, v0
	v_mov_b32_e32 v12, v0
	v_mov_b32_e32 v13, v0
	v_mov_b32_e32 v14, v0
	v_mov_b32_e32 v15, v0
	v_mov_b32_e32 v24, v0
	v_mov_b32_e32 v25, v0
	v_mov_b32_e32 v26, v0
	v_mov_b32_e32 v27, v0
	v_mov_b32_e32 v28, v0
	v_mov_b32_e32 v29, v0
	v_mov_b32_e32 v30, v0
	v_mov_b32_e32 v31, v0
	v_mov_b32_e32 v40, v0
	v_mov_b32_e32 v41, v0
	v_mov_b32_e32 v42, v0
	v_mov_b32_e32 v43, v0
	v_mov_b32_e32 v44, v0
	v_mov_b32_e32 v45, v0
	v_mov_b32_e32 v46, v0
	v_mov_b32_e32 v47, v0
	v_mov_b32_e32 v56, v0
	v_mov_b32_e32 v57, v0
	v_mov_b32_e32 v58, v0
	v_mov_b32_e32 v59, v0
	v_mov_b32_e32 v60, v0
	v_mov_b32_e32 v61, v0
	v_mov_b32_e32 v62, v0
	v_mov_b32_e32 v63, v0
	v_mov_b32_e32 v64, v0
	v_mov_b32_e32 v65, v0
	v_mov_b32_e32 v66, v0
	v_mov_b32_e32 v67, v0
	v_mov_b32_e32 v68, v0
	v_mov_b32_e32 v69, v0
	v_mov_b32_e32 v70, v0
	v_mov_b32_e32 v71, v0
	v_mov_b32_e32 v80, v0
	v_mov_b32_e32 v81, v0
	v_mov_b32_e32 v82, v0
	v_mov_b32_e32 v83, v0
	v_mov_b32_e32 v84, v0
	v_mov_b32_e32 v85, v0
	v_mov_b32_e32 v86, v0
	v_mov_b32_e32 v87, v0
	v_mov_b32_e32 v96, v0
	v_mov_b32_e32 v97, v0
	v_mov_b32_e32 v98, v0
	v_mov_b32_e32 v99, v0
	v_mov_b32_e32 v100, v0
	v_mov_b32_e32 v101, v0
	v_mov_b32_e32 v102, v0
	v_mov_b32_e32 v103, v0
	v_mov_b32_e32 v112, v0
	v_mov_b32_e32 v113, v0
	v_mov_b32_e32 v114, v0
	v_mov_b32_e32 v115, v0
	v_mov_b32_e32 v116, v0
	v_mov_b32_e32 v117, v0
	v_mov_b32_e32 v118, v0
	v_mov_b32_e32 v119, v0
	v_mov_b32_e32 v72, v0
	v_mov_b32_e32 v73, v0
	v_mov_b32_e32 v74, v0
	v_mov_b32_e32 v75, v0
	v_mov_b32_e32 v76, v0
	v_mov_b32_e32 v77, v0
	v_mov_b32_e32 v78, v0
	v_mov_b32_e32 v79, v0
	v_mov_b32_e32 v88, v0
	v_mov_b32_e32 v89, v0
	v_mov_b32_e32 v90, v0
	v_mov_b32_e32 v91, v0
	v_mov_b32_e32 v92, v0
	v_mov_b32_e32 v93, v0
	v_mov_b32_e32 v94, v0
	v_mov_b32_e32 v95, v0
	v_mov_b32_e32 v104, v0
	v_mov_b32_e32 v105, v0
	v_mov_b32_e32 v106, v0
	v_mov_b32_e32 v107, v0
	v_mov_b32_e32 v108, v0
	v_mov_b32_e32 v109, v0
	v_mov_b32_e32 v110, v0
	v_mov_b32_e32 v111, v0
	v_mov_b32_e32 v120, v0
	v_mov_b32_e32 v121, v0
	v_mov_b32_e32 v122, v0
	v_mov_b32_e32 v123, v0
	v_mov_b32_e32 v124, v0
	v_mov_b32_e32 v125, v0
	v_mov_b32_e32 v126, v0
	v_mov_b32_e32 v127, v0
	s_nop 0
	s_nop 0
	s_nop 0
	s_nop 0
	s_nop 0
	s_nop 0
	s_nop 0
	s_nop 0
	s_nop 0

; #define PG8_STAGE(bufoff, gbase, voff) do { _Pragma("unroll") for (int _i = 0; _i < 2; ++_i) \
;         __builtin_amdgcn_global_load_lds((const unsigned*)((const char*)(gbase) + (voff)[_i]), (PG8_LAS unsigned*)(lds + (bufoff) + ldsw + _i * 8192), 16, 0, 0); } while (0)
; #define PG8_WAIT_V(n) asm volatile("s_waitcnt vmcnt(" #n ")" ::: "memory")
; #define PG8_BAR __builtin_amdgcn_s_barrier()
; template <class Epi, class Sched, bool ALIGN_EPI = false, bool SP2 = false, bool MIDHOOK = false>
; __device__ __forceinline__ void gemm_phase(PG8_LAS unsigned char* lds, const Gemm g, const Sched& S, const Epi& E) {
;     ...
;     f32x4 acc[2][2][4][2];
; #pragma unroll
;     for (int a = 0; a < 2; ++a)
; #pragma unroll
;         for (int b = 0; b < 2; ++b)
; #pragma unroll
;             for (int m = 0; m < 4; ++m)
; #pragma unroll
;                 for (int n = 0; n < 2; ++n) acc[a][b][m][n] = (f32x4){0.f, 0.f, 0.f, 0.f};
;     bf16x8 At[4][2], B0[2][2], B1[2][2];
;     const char* cA = (const char*)g.A + (size_t)cur.pm * tstep; const char* cB = (const char*)g.Bt + (size_t)cur.pn * tstep;
;     S.a_ready(cur);
;     if constexpr (SP2) {
;         PG8_STAGE(PG8_SB(0, 0), cB, voffB); PG8_STAGE(PG8_SB(0, 1), cB + hstep, voffB); PG8_STAGE(PG8_SA(0, 0), cA, voffA); PG8_STAGE(PG8_SA(0, 1), cA + hstep, voffA);
;         if (wr == 1) PG8_BAR;
;         PG8_WAIT_V(2); PG8_BAR;
;         PG8_STAGE(PG8_SB(1, 0), cB + kstep, voffB); PG8_STAGE(PG8_SA(1, 0), cA + kstep, voffA); PG8_STAGE(PG8_SB(1, 1), cB + hstep + kstep, voffB);
;         PG8_WAIT_V(6); PG8_BAR;
;     } else {
;         PG8_STAGE(PG8_SB(0, 0), cB, voffB); PG8_STAGE(PG8_SA(0, 0), cA, voffA); PG8_STAGE(PG8_SB(0, 1), cB + hstep, voffB); PG8_STAGE(PG8_SA(0, 1), cA + hstep, voffA);
;         if (wr == 1) PG8_BAR;
;         PG8_WAIT_V(4); PG8_BAR;
;         PG8_STAGE(PG8_SB(1, 0), cB + kstep, voffB); PG8_STAGE(PG8_SA(1, 0), cA + kstep, voffA); PG8_STAGE(PG8_SB(1, 1), cB + hstep + kstep, voffB);
;         PG8_WAIT_V(6); PG8_BAR;
;     }
.LBB0_4174:
	s_mov_b64 s[8:9], 0x80
	s_add_i32 m0, s30, 0x18000
	v_lshl_add_u64 v[6:7], v[6:7], 0, s[8:9]
	s_and_b32 s3, s84, 3
	s_waitcnt vmcnt(2)
	s_barrier
	global_load_lds_dwordx4 v[6:7], off
	v_lshl_add_u64 v[4:5], v[4:5], 0, s[8:9]
	s_add_i32 m0, s30, 0x1a000
	s_add_i32 s35, s30, 0x8000
	s_add_i32 s36, s30, 0xa000
	global_load_lds_dwordx4 v[4:5], off
	v_lshl_add_u64 v[2:3], v[2:3], 0, s[8:9]
	s_mov_b32 m0, s35
	s_add_u32 s28, s0, 0x100080
	global_load_lds_dwordx4 v[2:3], off
	v_lshl_add_u64 v[0:1], v[0:1], 0, s[8:9]
	s_mov_b32 m0, s36
	s_addc_u32 s29, s1, 0
	global_load_lds_dwordx4 v[0:1], off
	s_add_i32 m0, s30, 0x1c000
	v_lshl_add_u64 v[0:1], s[28:29], 0, v[130:131]
	global_load_lds_dwordx4 v[0:1], off
	v_lshl_add_u64 v[0:1], s[28:29], 0, v[134:135]
	s_add_i32 m0, s30, 0x1e000
	s_add_u32 s22, s82, s22
	global_load_lds_dwordx4 v[0:1], off
	v_lshlrev_b32_e32 v0, 16, v8
	v_and_b32_e32 v0, 0xfffe0000, v0
	v_lshl_add_u32 v0, v9, 13, v0
	v_and_b32_e32 v1, 1, v8
	v_lshl_or_b32 v0, v1, 6, v0
	s_addc_u32 s23, s83, s23
	v_lshl_add_u32 v0, v10, 1, v0
	v_mov_b32_e32 v1, v131
	v_lshl_add_u64 v[0:1], s[22:23], 0, v[0:1]
	s_mov_b64 s[28:29], 0xe100080
	v_lshl_add_u64 v[136:137], v[0:1], 0, s[28:29]
	v_lshlrev_b32_e32 v0, 16, v11
	v_and_b32_e32 v15, 15, v140
	v_and_b32_e32 v16, 48, v140
	v_and_b32_e32 v0, 0xfffe0000, v0
	s_add_u32 s24, s82, s24
	v_lshl_or_b32 v146, s17, 6, v15
	v_and_b32_e32 v14, 0xfffffc00, v14
	v_lshl_or_b32 v15, v15, 6, v16
	v_lshlrev_b32_e32 v16, 2, v140
	v_lshl_add_u32 v0, v12, 13, v0
	v_and_b32_e32 v1, 1, v11
	s_addc_u32 s25, s83, s25
	v_lshl_add_u32 v17, s17, 13, v14
	v_and_b32_e32 v16, 32, v16
	v_lshl_add_u32 v14, s3, 12, v14
	v_lshl_or_b32 v0, v1, 6, v0
	s_add_u32 s37, s24, 0x1800100
	v_bitop3_b32 v14, v15, v14, v16 bitop3:0xde
	s_waitcnt vmcnt(6)
	v_lshl_add_u32 v0, v13, 1, v0
	v_mov_b32_e32 v1, v131
	s_addc_u32 s38, s25, 0
	s_add_i32 s42, 0, 0x10000
	s_add_i32 s44, 0, 0x14000
	s_add_i32 s46, 0, 0x18000
	s_add_i32 s48, 0, 0x1c000
	v_bitop3_b32 v17, v15, v17, v16 bitop3:0xde
	v_lshl_add_u64 v[0:1], s[22:23], 0, v[0:1]
	v_add_u32_e32 v141, s42, v14
	v_add_u32_e32 v142, s44, v14
	s_add_i32 s42, s42, s26
	s_add_i32 s44, s44, s26
	v_add_u32_e32 v144, s46, v14
	v_add_u32_e32 v145, s48, v14
	s_add_i32 s46, s46, s26
	s_add_i32 s48, s48, s26
	v_lshl_add_u64 v[138:139], v[0:1], 0, s[28:29]
	s_mov_b32 s39, -2
	s_mov_b64 s[24:25], 0
	v_add_u32_e32 v143, 0, v17
	s_add_i32 s40, s30, 0xc000
	s_add_i32 s41, s30, 0xe000
	s_add_i32 s43, s42, 0x2000
	s_add_i32 s45, s44, 0x2000
	s_add_i32 s47, s46, 0x2000
	s_add_i32 s49, s48, 0x2000
	v_mov_b32_e32 v72, v131
	v_mov_b32_e32 v73, v131
	v_mov_b32_e32 v74, v131
	v_mov_b32_e32 v75, v131
	v_mov_b32_e32 v76, v131
	v_mov_b32_e32 v77, v131
	v_mov_b32_e32 v78, v131
	v_mov_b32_e32 v79, v131
	v_mov_b32_e32 v56, v131
	v_mov_b32_e32 v57, v131
	v_mov_b32_e32 v58, v131
	v_mov_b32_e32 v59, v131
	v_mov_b32_e32 v60, v131
	v_mov_b32_e32 v61, v131
	v_mov_b32_e32 v62, v131
	v_mov_b32_e32 v63, v131
	v_mov_b32_e32 v40, v131
	v_mov_b32_e32 v41, v131
	v_mov_b32_e32 v42, v131
	v_mov_b32_e32 v43, v131
	v_mov_b32_e32 v44, v131
	v_mov_b32_e32 v45, v131
	v_mov_b32_e32 v46, v131
	v_mov_b32_e32 v47, v131
	v_mov_b32_e32 v32, v131
	v_mov_b32_e32 v33, v131
	v_mov_b32_e32 v34, v131
	v_mov_b32_e32 v35, v131
	v_mov_b32_e32 v36, v131
	v_mov_b32_e32 v37, v131
	v_mov_b32_e32 v38, v131
	v_mov_b32_e32 v39, v131
	v_mov_b32_e32 v116, v131
	v_mov_b32_e32 v117, v131
	v_mov_b32_e32 v118, v131
	v_mov_b32_e32 v119, v131
	v_mov_b32_e32 v120, v131
	v_mov_b32_e32 v121, v131
	v_mov_b32_e32 v122, v131
	v_mov_b32_e32 v123, v131
	v_mov_b32_e32 v112, v131
	v_mov_b32_e32 v113, v131
	v_mov_b32_e32 v114, v131
	v_mov_b32_e32 v115, v131
	v_mov_b32_e32 v124, v131
	v_mov_b32_e32 v125, v131
	v_mov_b32_e32 v126, v131
	v_mov_b32_e32 v127, v131
	v_mov_b32_e32 v104, v131
	v_mov_b32_e32 v105, v131
	v_mov_b32_e32 v106, v131
	v_mov_b32_e32 v107, v131
	v_mov_b32_e32 v108, v131
	v_mov_b32_e32 v109, v131
	v_mov_b32_e32 v110, v131
	v_mov_b32_e32 v111, v131
	v_mov_b32_e32 v96, v131
	v_mov_b32_e32 v97, v131
	v_mov_b32_e32 v98, v131
	v_mov_b32_e32 v99, v131
	v_mov_b32_e32 v100, v131
	v_mov_b32_e32 v101, v131
	v_mov_b32_e32 v102, v131
	v_mov_b32_e32 v103, v131
	v_mov_b32_e32 v24, v131
	v_mov_b32_e32 v25, v131
	v_mov_b32_e32 v26, v131
	v_mov_b32_e32 v27, v131
	v_mov_b32_e32 v28, v131
	v_mov_b32_e32 v29, v131
	v_mov_b32_e32 v30, v131
	v_mov_b32_e32 v31, v131
	v_mov_b32_e32 v16, v131
	v_mov_b32_e32 v17, v131
	v_mov_b32_e32 v18, v131
	v_mov_b32_e32 v19, v131
	v_mov_b32_e32 v20, v131
	v_mov_b32_e32 v21, v131
	v_mov_b32_e32 v22, v131
	v_mov_b32_e32 v23, v131
	v_mov_b32_e32 v8, v131
	v_mov_b32_e32 v9, v131
	v_mov_b32_e32 v10, v131
	v_mov_b32_e32 v11, v131
	v_mov_b32_e32 v12, v131
	v_mov_b32_e32 v13, v131
	v_mov_b32_e32 v14, v131
	v_mov_b32_e32 v15, v131
	v_mov_b32_e32 v0, v131
	v_mov_b32_e32 v1, v131
	v_mov_b32_e32 v2, v131
	v_mov_b32_e32 v3, v131
	v_mov_b32_e32 v4, v131
	v_mov_b32_e32 v5, v131
	v_mov_b32_e32 v6, v131
	v_mov_b32_e32 v7, v131
	v_mov_b32_e32 v88, v131
	v_mov_b32_e32 v89, v131
	v_mov_b32_e32 v90, v131
	v_mov_b32_e32 v91, v131
	v_mov_b32_e32 v92, v131
	v_mov_b32_e32 v93, v131
	v_mov_b32_e32 v94, v131
	v_mov_b32_e32 v95, v131
	v_mov_b32_e32 v80, v131
	v_mov_b32_e32 v81, v131
	v_mov_b32_e32 v82, v131
	v_mov_b32_e32 v83, v131
	v_mov_b32_e32 v84, v131
	v_mov_b32_e32 v85, v131
	v_mov_b32_e32 v86, v131
	v_mov_b32_e32 v87, v131
	v_mov_b32_e32 v64, v131
	v_mov_b32_e32 v65, v131
	v_mov_b32_e32 v66, v131
	v_mov_b32_e32 v67, v131
	v_mov_b32_e32 v68, v131
	v_mov_b32_e32 v69, v131
	v_mov_b32_e32 v70, v131
	v_mov_b32_e32 v71, v131
	v_mov_b32_e32 v48, v131
	v_mov_b32_e32 v49, v131
	v_mov_b32_e32 v50, v131
	v_mov_b32_e32 v51, v131
	v_mov_b32_e32 v52, v131
	v_mov_b32_e32 v53, v131
	v_mov_b32_e32 v54, v131
	v_mov_b32_e32 v55, v131
	s_barrier
	s_nop 0
	s_nop 0
	s_nop 0
	s_nop 0
